# v91 + per-iteration s_waitcnt vmcnt(0) removed from the QKV main K-loop (the template's counted waits already retire each slot)
# baseline (speedup 1.0000x reference)
; #define PG8_STAGE(bufoff, gbase, voff) do { _Pragma("unroll") for (int _i = 0; _i < 2; ++_i) \
;         __builtin_amdgcn_global_load_lds((const unsigned*)((const char*)(gbase) + (voff)[_i]), (PG8_LAS unsigned*)(lds + (bufoff) + ldsw + _i * 8192), 16, 0, 0); } while (0)
; #define PG8_LDA(dst, b, h) do { _Pragma("unroll") for (int m = 0; m < 4; ++m) _Pragma("unroll") for (int k = 0; k < 2; ++k) dst[m][k] = *(const PG8_LAS bf16x8*)(lds + PG8_SA(b, h) + aoff + m * 2048 + k * 1024); } while (0)
; #define PG8_LDB(dst, b, h) do { _Pragma("unroll") for (int n = 0; n < 2; ++n) _Pragma("unroll") for (int k = 0; k < 2; ++k) dst[n][k] = *(const PG8_LAS bf16x8*)(lds + PG8_SB(b, h) + boff + n * 2048 + k * 1024); } while (0)
; #define PG8_MMA(ai, bj, At, Bt) do { __builtin_amdgcn_s_setprio(1); _Pragma("unroll") for (int m = 0; m < 4; ++m) _Pragma("unroll") for (int n = 0; n < 2; ++n) _Pragma("unroll") for (int k = 0; k < 2; ++k) \
;         acc[ai][bj][m][n] = mma16<Epi::I8>(Bt[n][k], At[m][k], acc[ai][bj][m][n]); __builtin_amdgcn_s_setprio(0); } while (0)
; #define PG8_WAIT_V(n) asm volatile("s_waitcnt vmcnt(" #n ")" ::: "memory")
; #define PG8_WAIT_L(n) asm volatile("s_waitcnt lgkmcnt(" #n ")" ::: "memory")
; #define PG8_BAR __builtin_amdgcn_s_barrier()
; template <class Epi, class Sched, bool ALIGN_EPI = false, bool SP2 = false>
; __device__ __forceinline__ void gemm_phase(PG8_LAS unsigned char* lds, const Gemm g, const Sched& S, const Epi& E) {
;     ...
;             const bool last = (t == nt - 2);
;             const char* a1 = cA + (size_t)(t + 1) * kstep;
;             const char* a2 = last ? nA : cA + (size_t)(t + 2) * kstep; const char* b2 = last ? nB : cB + (size_t)(t + 2) * kstep;
;             const char* a3 = a2 + kstep; const char* b3 = b2 + kstep;
;             if (last && has_next) S.a_ready(nxt);
;             if constexpr (SP2) {
;             PG8_LDB(B0, 0, 0); PG8_LDB(B1, 0, 1); PG8_SCHED; PG8_LDA(At, 0, 0); PG8_STAGE(PG8_SA(1, 1), a1 + hstep, voffA);
;             PG8_WAIT_V(8); PG8_WAIT_L(0); PG8_BAR; PG8_MMA(0, 0, At, B0); PG8_MMA(0, 1, At, B1); PG8_BAR; PG8_SCHED;
;             PG8_LDA(At, 0, 1); PG8_STAGE(PG8_SB(0, 0), b2, voffB); PG8_STAGE(PG8_SB(0, 1), b2 + hstep, voffB); PG8_STAGE(PG8_SA(0, 0), a2, voffA);
;             PG8_WAIT_V(8); PG8_WAIT_L(0); PG8_BAR; PG8_MMA(1, 0, At, B0); PG8_MMA(1, 1, At, B1); PG8_BAR; PG8_SCHED;
.LBB0_291:
	s_add_u32 s84, s8, 0x100
	s_addc_u32 s85, s9, 0
	s_add_i32 s66, 0, 0x10000
	s_cmp_eq_u32 s10, 12
	s_cselect_b32 vcc_hi, s5, s85
	s_cselect_b32 vcc_lo, s7, s84
	s_cselect_b32 s97, s11, s68
	s_cselect_b32 s96, s67, s69
	s_add_i32 s70, 0, 0x14000
	v_add_u32_e32 v110, s66, v175
	v_add_u32_e32 v168, s70, v175
	ds_read_b128 v[66:69], v110
	ds_read_b128 v[70:73], v110 offset:1024
	ds_read_b128 v[106:109], v110 offset:2048
	ds_read_b128 v[110:113], v110 offset:3072
	ds_read_b128 v[114:117], v168
	ds_read_b128 v[118:121], v168 offset:1024
	ds_read_b128 v[126:129], v168 offset:2048
	ds_read_b128 v[178:181], v168 offset:3072
	v_lshl_add_u64 v[168:169], s[8:9], 0, v[164:165]
	s_add_i32 m0, s1, 0xc000
	ds_read_b128 v[182:185], v177
	ds_read_b128 v[186:189], v177 offset:1024
	ds_read_b128 v[190:193], v177 offset:2048
	ds_read_b128 v[194:197], v177 offset:3072
	ds_read_b128 v[198:201], v177 offset:4096
	ds_read_b128 v[210:213], v177 offset:5120
	ds_read_b128 v[214:217], v177 offset:6144
	ds_read_b128 v[218:221], v177 offset:7168
	global_load_lds_dwordx4 v[168:169], off
	v_lshl_add_u64 v[168:169], s[8:9], 0, v[166:167]
	s_add_i32 m0, s1, 0xe000
	s_nop 0
	global_load_lds_dwordx4 v[168:169], off
	s_waitcnt vmcnt(8)
	s_waitcnt lgkmcnt(0)
	s_barrier
	s_waitcnt lgkmcnt(0)
	v_mfma_i32_16x16x64_i8 v[154:157], v[66:69], v[182:185], v[154:157]
	v_mfma_i32_16x16x64_i8 v[154:157], v[70:73], v[186:189], v[154:157]
	v_mfma_i32_16x16x64_i8 v[146:149], v[110:113], v[186:189], v[146:149]
	v_mfma_i32_16x16x64_i8 v[146:149], v[106:109], v[182:185], v[146:149]
	v_mfma_i32_16x16x64_i8 v[138:141], v[106:109], v[190:193], v[138:141]
	v_mfma_i32_16x16x64_i8 v[138:141], v[110:113], v[194:197], v[138:141]
	v_mfma_i32_16x16x64_i8 v[150:153], v[70:73], v[194:197], v[150:153]
	v_mfma_i32_16x16x64_i8 v[150:153], v[66:69], v[190:193], v[150:153]
	v_mfma_i32_16x16x64_i8 v[142:145], v[66:69], v[198:201], v[142:145]
	v_mfma_i32_16x16x64_i8 v[142:145], v[70:73], v[210:213], v[142:145]
	v_mfma_i32_16x16x64_i8 v[130:133], v[110:113], v[210:213], v[130:133]
	v_mfma_i32_16x16x64_i8 v[130:133], v[106:109], v[198:201], v[130:133]
	v_mfma_i32_16x16x64_i8 v[122:125], v[106:109], v[214:217], v[122:125]
	v_mfma_i32_16x16x64_i8 v[122:125], v[110:113], v[218:221], v[122:125]
	v_mfma_i32_16x16x64_i8 v[134:137], v[70:73], v[218:221], v[134:137]
	v_mfma_i32_16x16x64_i8 v[134:137], v[66:69], v[214:217], v[134:137]
	v_mfma_i32_16x16x64_i8 v[74:77], v[126:129], v[214:217], v[74:77]
	v_mfma_i32_16x16x64_i8 v[74:77], v[178:181], v[218:221], v[74:77]
	v_mfma_i32_16x16x64_i8 v[94:97], v[178:181], v[186:189], v[94:97]
	v_mfma_i32_16x16x64_i8 v[94:97], v[126:129], v[182:185], v[94:97]
	v_mfma_i32_16x16x64_i8 v[102:105], v[114:117], v[182:185], v[102:105]
	v_mfma_i32_16x16x64_i8 v[102:105], v[118:121], v[186:189], v[102:105]
	v_mfma_i32_16x16x64_i8 v[98:101], v[118:121], v[194:197], v[98:101]
	v_mfma_i32_16x16x64_i8 v[98:101], v[114:117], v[190:193], v[98:101]
	v_mfma_i32_16x16x64_i8 v[86:89], v[126:129], v[190:193], v[86:89]
	v_mfma_i32_16x16x64_i8 v[86:89], v[178:181], v[194:197], v[86:89]
	v_mfma_i32_16x16x64_i8 v[78:81], v[178:181], v[210:213], v[78:81]
	v_mfma_i32_16x16x64_i8 v[78:81], v[126:129], v[198:201], v[78:81]
	v_mfma_i32_16x16x64_i8 v[90:93], v[114:117], v[198:201], v[90:93]
	v_mfma_i32_16x16x64_i8 v[90:93], v[118:121], v[210:213], v[90:93]
	v_mfma_i32_16x16x64_i8 v[82:85], v[118:121], v[218:221], v[82:85]
	v_mfma_i32_16x16x64_i8 v[82:85], v[114:117], v[214:217], v[82:85]
	s_barrier
	s_add_i32 s8, s66, s81
	v_lshl_add_u64 v[168:169], s[96:97], 0, v[0:1]
	s_mov_b32 m0, s8
	ds_read_b128 v[182:185], v177 offset:16384
	ds_read_b128 v[186:189], v177 offset:17408
	ds_read_b128 v[190:193], v177 offset:18432
	ds_read_b128 v[194:197], v177 offset:19456
	ds_read_b128 v[198:201], v177 offset:20480
	ds_read_b128 v[210:213], v177 offset:21504
	ds_read_b128 v[214:217], v177 offset:22528
	ds_read_b128 v[218:221], v177 offset:23552
	global_load_lds_dwordx4 v[168:169], off
	s_add_i32 m0, s8, 0x2000
	s_add_u32 s8, s96, 0x40000
	v_lshl_add_u64 v[206:207], s[96:97], 0, v[158:159]
	s_addc_u32 s9, s97, 0
	s_add_i32 s66, s70, s81
	global_load_lds_dwordx4 v[206:207], off
	v_lshl_add_u64 v[222:223], s[8:9], 0, v[0:1]
	s_mov_b32 m0, s66
	v_lshl_add_u64 v[224:225], vcc, 0, v[160:161]
	global_load_lds_dwordx4 v[222:223], off
	v_lshl_add_u64 v[222:223], s[8:9], 0, v[158:159]
	s_add_i32 m0, s66, 0x2000
	s_nop 0
	global_load_lds_dwordx4 v[222:223], off
	v_lshl_add_u64 v[222:223], vcc, 0, v[162:163]
	s_mov_b32 m0, s1
	s_nop 0
	global_load_lds_dwordx4 v[222:223], off
	s_mov_b32 m0, s58
	s_nop 0
	global_load_lds_dwordx4 v[224:225], off
	s_waitcnt vmcnt(8)
	s_waitcnt lgkmcnt(0)
	s_barrier
; #define PG8_STAGE(bufoff, gbase, voff) do { _Pragma("unroll") for (int _i = 0; _i < 2; ++_i) \
;         __builtin_amdgcn_global_load_lds((const unsigned*)((const char*)(gbase) + (voff)[_i]), (PG8_LAS unsigned*)(lds + (bufoff) + ldsw + _i * 8192), 16, 0, 0); } while (0)
; #define PG8_LDA(dst, b, h) do { _Pragma("unroll") for (int m = 0; m < 4; ++m) _Pragma("unroll") for (int k = 0; k < 2; ++k) dst[m][k] = *(const PG8_LAS bf16x8*)(lds + PG8_SA(b, h) + aoff + m * 2048 + k * 1024); } while (0)
; #define PG8_LDB(dst, b, h) do { _Pragma("unroll") for (int n = 0; n < 2; ++n) _Pragma("unroll") for (int k = 0; k < 2; ++k) dst[n][k] = *(const PG8_LAS bf16x8*)(lds + PG8_SB(b, h) + boff + n * 2048 + k * 1024); } while (0)
; #define PG8_MMA(ai, bj, At, Bt) do { __builtin_amdgcn_s_setprio(1); _Pragma("unroll") for (int m = 0; m < 4; ++m) _Pragma("unroll") for (int n = 0; n < 2; ++n) _Pragma("unroll") for (int k = 0; k < 2; ++k) \
;         acc[ai][bj][m][n] = mma16<Epi::I8>(Bt[n][k], At[m][k], acc[ai][bj][m][n]); __builtin_amdgcn_s_setprio(0); } while (0)
; #define PG8_WAIT_V(n) asm volatile("s_waitcnt vmcnt(" #n ")" ::: "memory")
; #define PG8_WAIT_L(n) asm volatile("s_waitcnt lgkmcnt(" #n ")" ::: "memory")
; #define PG8_BAR __builtin_amdgcn_s_barrier()
; #define PG8_SCHED __builtin_amdgcn_sched_barrier(0)
; template <class Epi, class Sched, bool ALIGN_EPI = false, bool SP2 = false>
; __device__ __forceinline__ void gemm_phase(PG8_LAS unsigned char* lds, const Gemm g, const Sched& S, const Epi& E) {
;     ...
;             PG8_WAIT_V(8); PG8_WAIT_L(0); PG8_BAR; PG8_MMA(0, 0, At, B0); PG8_MMA(0, 1, At, B1); PG8_BAR; PG8_SCHED;
;             PG8_LDA(At, 0, 1); PG8_STAGE(PG8_SB(0, 0), b2, voffB); PG8_STAGE(PG8_SB(0, 1), b2 + hstep, voffB); PG8_STAGE(PG8_SA(0, 0), a2, voffA);
;             PG8_WAIT_V(8); PG8_WAIT_L(0); PG8_BAR; PG8_MMA(1, 0, At, B0); PG8_MMA(1, 1, At, B1); PG8_BAR; PG8_SCHED;
;             PG8_LDB(B0, 1, 0); PG8_LDB(B1, 1, 1); PG8_SCHED; PG8_LDA(At, 1, 0); PG8_STAGE(PG8_SA(0, 1), a2 + hstep, voffA);
;             PG8_WAIT_V(8); PG8_WAIT_L(0); PG8_BAR; PG8_MMA(0, 0, At, B0); PG8_MMA(0, 1, At, B1); PG8_BAR; PG8_SCHED;
	s_waitcnt lgkmcnt(0)
	v_mfma_i32_16x16x64_i8 v[62:65], v[66:69], v[182:185], v[62:65]
	v_mfma_i32_16x16x64_i8 v[62:65], v[70:73], v[186:189], v[62:65]
	v_mfma_i32_16x16x64_i8 v[54:57], v[110:113], v[186:189], v[54:57]
	v_mfma_i32_16x16x64_i8 v[54:57], v[106:109], v[182:185], v[54:57]
	v_mfma_i32_16x16x64_i8 v[46:49], v[106:109], v[190:193], v[46:49]
	v_mfma_i32_16x16x64_i8 v[46:49], v[110:113], v[194:197], v[46:49]
	v_mfma_i32_16x16x64_i8 v[58:61], v[70:73], v[194:197], v[58:61]
	v_mfma_i32_16x16x64_i8 v[58:61], v[66:69], v[190:193], v[58:61]
	v_mfma_i32_16x16x64_i8 v[50:53], v[66:69], v[198:201], v[50:53]
	v_mfma_i32_16x16x64_i8 v[50:53], v[70:73], v[210:213], v[50:53]
	v_mfma_i32_16x16x64_i8 v[38:41], v[110:113], v[210:213], v[38:41]
	v_mfma_i32_16x16x64_i8 v[38:41], v[106:109], v[198:201], v[38:41]
	v_mfma_i32_16x16x64_i8 v[34:37], v[106:109], v[214:217], v[34:37]
	v_mfma_i32_16x16x64_i8 v[34:37], v[110:113], v[218:221], v[34:37]
	v_mfma_i32_16x16x64_i8 v[42:45], v[70:73], v[218:221], v[42:45]
	v_mfma_i32_16x16x64_i8 v[42:45], v[66:69], v[214:217], v[42:45]
	v_mfma_i32_16x16x64_i8 v[2:5], v[126:129], v[214:217], v[2:5]
	v_mfma_i32_16x16x64_i8 v[2:5], v[178:181], v[218:221], v[2:5]
	v_mfma_i32_16x16x64_i8 v[22:25], v[178:181], v[186:189], v[22:25]
	v_mfma_i32_16x16x64_i8 v[22:25], v[126:129], v[182:185], v[22:25]
	v_mfma_i32_16x16x64_i8 v[30:33], v[114:117], v[182:185], v[30:33]
	v_mfma_i32_16x16x64_i8 v[30:33], v[118:121], v[186:189], v[30:33]
	v_mfma_i32_16x16x64_i8 v[26:29], v[118:121], v[194:197], v[26:29]
	v_mfma_i32_16x16x64_i8 v[26:29], v[114:117], v[190:193], v[26:29]
	v_mfma_i32_16x16x64_i8 v[14:17], v[126:129], v[190:193], v[14:17]
	v_mfma_i32_16x16x64_i8 v[14:17], v[178:181], v[194:197], v[14:17]
	v_mfma_i32_16x16x64_i8 v[6:9], v[178:181], v[210:213], v[6:9]
	v_mfma_i32_16x16x64_i8 v[6:9], v[126:129], v[198:201], v[6:9]
	v_mfma_i32_16x16x64_i8 v[18:21], v[114:117], v[198:201], v[18:21]
	v_mfma_i32_16x16x64_i8 v[18:21], v[118:121], v[210:213], v[18:21]
	v_mfma_i32_16x16x64_i8 v[10:13], v[118:121], v[218:221], v[10:13]
	v_mfma_i32_16x16x64_i8 v[10:13], v[114:117], v[214:217], v[10:13]
	s_barrier
	s_add_i32 s66, 0, 0x18000
	s_add_i32 s70, 0, 0x1c000
	v_add_u32_e32 v110, s66, v175
	v_add_u32_e32 v170, s70, v175
	ds_read_b128 v[66:69], v110
	ds_read_b128 v[70:73], v110 offset:1024
	ds_read_b128 v[106:109], v110 offset:2048
	ds_read_b128 v[110:113], v110 offset:3072
	ds_read_b128 v[114:117], v170
	ds_read_b128 v[118:121], v170 offset:1024
	ds_read_b128 v[126:129], v170 offset:2048
	ds_read_b128 v[178:181], v170 offset:3072
	s_add_u32 s8, vcc_lo, 0x40000
	s_addc_u32 s9, vcc_hi, 0
	s_mov_b32 m0, s80
	v_lshl_add_u64 v[226:227], s[8:9], 0, v[162:163]
	ds_read_b128 v[182:185], v177 offset:32768
	ds_read_b128 v[186:189], v177 offset:33792
	ds_read_b128 v[190:193], v177 offset:34816
	ds_read_b128 v[194:197], v177 offset:35840
	ds_read_b128 v[198:201], v177 offset:36864
	ds_read_b128 v[210:213], v177 offset:37888
	ds_read_b128 v[214:217], v177 offset:38912
	ds_read_b128 v[218:221], v177 offset:39936
	global_load_lds_dwordx4 v[226:227], off
	v_lshl_add_u64 v[226:227], s[8:9], 0, v[160:161]
	s_mov_b32 m0, s0
	s_nop 0
	global_load_lds_dwordx4 v[226:227], off
	s_waitcnt vmcnt(8)
	s_waitcnt lgkmcnt(0)
	s_barrier
	s_waitcnt lgkmcnt(0)
	v_mfma_i32_16x16x64_i8 v[154:157], v[66:69], v[182:185], v[154:157]
	v_mfma_i32_16x16x64_i8 v[154:157], v[70:73], v[186:189], v[154:157]
	v_mfma_i32_16x16x64_i8 v[146:149], v[110:113], v[186:189], v[146:149]
	v_mfma_i32_16x16x64_i8 v[146:149], v[106:109], v[182:185], v[146:149]
	v_mfma_i32_16x16x64_i8 v[138:141], v[106:109], v[190:193], v[138:141]
	v_mfma_i32_16x16x64_i8 v[138:141], v[110:113], v[194:197], v[138:141]
	v_mfma_i32_16x16x64_i8 v[150:153], v[70:73], v[194:197], v[150:153]
	v_mfma_i32_16x16x64_i8 v[150:153], v[66:69], v[190:193], v[150:153]
	v_mfma_i32_16x16x64_i8 v[142:145], v[66:69], v[198:201], v[142:145]
	v_mfma_i32_16x16x64_i8 v[142:145], v[70:73], v[210:213], v[142:145]
	v_mfma_i32_16x16x64_i8 v[130:133], v[110:113], v[210:213], v[130:133]
	v_mfma_i32_16x16x64_i8 v[130:133], v[106:109], v[198:201], v[130:133]
	v_mfma_i32_16x16x64_i8 v[122:125], v[106:109], v[214:217], v[122:125]
	v_mfma_i32_16x16x64_i8 v[122:125], v[110:113], v[218:221], v[122:125]
	v_mfma_i32_16x16x64_i8 v[134:137], v[70:73], v[218:221], v[134:137]
	v_mfma_i32_16x16x64_i8 v[134:137], v[66:69], v[214:217], v[134:137]
	v_mfma_i32_16x16x64_i8 v[74:77], v[126:129], v[214:217], v[74:77]
	v_mfma_i32_16x16x64_i8 v[74:77], v[178:181], v[218:221], v[74:77]
	v_mfma_i32_16x16x64_i8 v[94:97], v[178:181], v[186:189], v[94:97]
	v_mfma_i32_16x16x64_i8 v[94:97], v[126:129], v[182:185], v[94:97]
	v_mfma_i32_16x16x64_i8 v[102:105], v[114:117], v[182:185], v[102:105]
	v_mfma_i32_16x16x64_i8 v[102:105], v[118:121], v[186:189], v[102:105]
	v_mfma_i32_16x16x64_i8 v[98:101], v[118:121], v[194:197], v[98:101]
	v_mfma_i32_16x16x64_i8 v[98:101], v[114:117], v[190:193], v[98:101]
	v_mfma_i32_16x16x64_i8 v[86:89], v[126:129], v[190:193], v[86:89]
	v_mfma_i32_16x16x64_i8 v[86:89], v[178:181], v[194:197], v[86:89]
	v_mfma_i32_16x16x64_i8 v[78:81], v[178:181], v[210:213], v[78:81]
	v_mfma_i32_16x16x64_i8 v[78:81], v[126:129], v[198:201], v[78:81]
	v_mfma_i32_16x16x64_i8 v[90:93], v[114:117], v[198:201], v[90:93]
	v_mfma_i32_16x16x64_i8 v[90:93], v[118:121], v[210:213], v[90:93]
	v_mfma_i32_16x16x64_i8 v[82:85], v[118:121], v[218:221], v[82:85]
	v_mfma_i32_16x16x64_i8 v[82:85], v[114:117], v[214:217], v[82:85]
	s_barrier
; #define PG8_STAGE(bufoff, gbase, voff) do { _Pragma("unroll") for (int _i = 0; _i < 2; ++_i) \
;         __builtin_amdgcn_global_load_lds((const unsigned*)((const char*)(gbase) + (voff)[_i]), (PG8_LAS unsigned*)(lds + (bufoff) + ldsw + _i * 8192), 16, 0, 0); } while (0)
; #define PG8_LDA(dst, b, h) do { _Pragma("unroll") for (int m = 0; m < 4; ++m) _Pragma("unroll") for (int k = 0; k < 2; ++k) dst[m][k] = *(const PG8_LAS bf16x8*)(lds + PG8_SA(b, h) + aoff + m * 2048 + k * 1024); } while (0)
; #define PG8_MMA(ai, bj, At, Bt) do { __builtin_amdgcn_s_setprio(1); _Pragma("unroll") for (int m = 0; m < 4; ++m) _Pragma("unroll") for (int n = 0; n < 2; ++n) _Pragma("unroll") for (int k = 0; k < 2; ++k) \
;         acc[ai][bj][m][n] = mma16<Epi::I8>(Bt[n][k], At[m][k], acc[ai][bj][m][n]); __builtin_amdgcn_s_setprio(0); } while (0)
; #define PG8_WAIT_V(n) asm volatile("s_waitcnt vmcnt(" #n ")" ::: "memory")
; #define PG8_WAIT_L(n) asm volatile("s_waitcnt lgkmcnt(" #n ")" ::: "memory")
; #define PG8_BAR __builtin_amdgcn_s_barrier()
; #define PG8_SCHED __builtin_amdgcn_sched_barrier(0)
; template <class Epi, class Sched, bool ALIGN_EPI = false, bool SP2 = false>
; __device__ __forceinline__ void gemm_phase(PG8_LAS unsigned char* lds, const Gemm g, const Sched& S, const Epi& E) {
;     ...
;             PG8_LDA(At, 1, 1); PG8_STAGE(PG8_SB(1, 0), b3, voffB); PG8_STAGE(PG8_SB(1, 1), b3 + hstep, voffB); PG8_STAGE(PG8_SA(1, 0), a3, voffA);
;             PG8_WAIT_V(8); PG8_WAIT_L(0); PG8_BAR; PG8_MMA(1, 0, At, B0); PG8_MMA(1, 1, At, B1); PG8_BAR; PG8_SCHED;
	s_add_i32 s8, s66, s81
	v_lshl_add_u64 v[168:169], v[168:169], 0, s[92:93]
	s_mov_b32 m0, s8
	ds_read_b128 v[182:185], v177 offset:49152
	ds_read_b128 v[186:189], v177 offset:50176
	ds_read_b128 v[190:193], v177 offset:51200
	ds_read_b128 v[194:197], v177 offset:52224
	ds_read_b128 v[198:201], v177 offset:53248
	ds_read_b128 v[210:213], v177 offset:54272
	ds_read_b128 v[214:217], v177 offset:55296
	ds_read_b128 v[218:221], v177 offset:56320
	global_load_lds_dwordx4 v[168:169], off
	s_add_i32 m0, s8, 0x2000
	s_add_u32 s8, s96, 0x40080
	v_lshl_add_u64 v[168:169], v[206:207], 0, s[92:93]
	s_addc_u32 s9, s97, 0
	s_add_i32 s66, s70, s81
	global_load_lds_dwordx4 v[168:169], off
	v_lshl_add_u64 v[168:169], s[8:9], 0, v[0:1]
	s_mov_b32 m0, s66
	s_nop 0
	global_load_lds_dwordx4 v[168:169], off
	v_lshl_add_u64 v[168:169], s[8:9], 0, v[158:159]
	s_add_i32 m0, s66, 0x2000
	s_nop 0
	global_load_lds_dwordx4 v[168:169], off
	v_lshl_add_u64 v[168:169], v[222:223], 0, s[92:93]
	s_mov_b32 m0, s13
	s_nop 0
	global_load_lds_dwordx4 v[168:169], off
	v_lshl_add_u64 v[168:169], v[224:225], 0, s[92:93]
	s_mov_b32 m0, s12
	s_nop 0
	global_load_lds_dwordx4 v[168:169], off
	s_waitcnt vmcnt(8)
	s_waitcnt lgkmcnt(0)
	s_barrier
	s_waitcnt lgkmcnt(0)
	v_mfma_i32_16x16x64_i8 v[62:65], v[66:69], v[182:185], v[62:65]
	v_mfma_i32_16x16x64_i8 v[62:65], v[70:73], v[186:189], v[62:65]
	v_mfma_i32_16x16x64_i8 v[54:57], v[110:113], v[186:189], v[54:57]
	v_mfma_i32_16x16x64_i8 v[54:57], v[106:109], v[182:185], v[54:57]
	v_mfma_i32_16x16x64_i8 v[46:49], v[106:109], v[190:193], v[46:49]
	v_mfma_i32_16x16x64_i8 v[46:49], v[110:113], v[194:197], v[46:49]
	v_mfma_i32_16x16x64_i8 v[58:61], v[70:73], v[194:197], v[58:61]
	v_mfma_i32_16x16x64_i8 v[58:61], v[66:69], v[190:193], v[58:61]
	v_mfma_i32_16x16x64_i8 v[50:53], v[66:69], v[198:201], v[50:53]
	v_mfma_i32_16x16x64_i8 v[50:53], v[70:73], v[210:213], v[50:53]
	v_mfma_i32_16x16x64_i8 v[38:41], v[110:113], v[210:213], v[38:41]
	v_mfma_i32_16x16x64_i8 v[38:41], v[106:109], v[198:201], v[38:41]
	v_mfma_i32_16x16x64_i8 v[34:37], v[106:109], v[214:217], v[34:37]
	v_mfma_i32_16x16x64_i8 v[34:37], v[110:113], v[218:221], v[34:37]
	v_mfma_i32_16x16x64_i8 v[42:45], v[70:73], v[218:221], v[42:45]
	v_mfma_i32_16x16x64_i8 v[42:45], v[66:69], v[214:217], v[42:45]
	v_mfma_i32_16x16x64_i8 v[2:5], v[126:129], v[214:217], v[2:5]
	v_mfma_i32_16x16x64_i8 v[2:5], v[178:181], v[218:221], v[2:5]
	v_mfma_i32_16x16x64_i8 v[22:25], v[178:181], v[186:189], v[22:25]
	v_mfma_i32_16x16x64_i8 v[22:25], v[126:129], v[182:185], v[22:25]
	v_mfma_i32_16x16x64_i8 v[30:33], v[114:117], v[182:185], v[30:33]
	v_mfma_i32_16x16x64_i8 v[30:33], v[118:121], v[186:189], v[30:33]
	v_mfma_i32_16x16x64_i8 v[26:29], v[118:121], v[194:197], v[26:29]
	v_mfma_i32_16x16x64_i8 v[26:29], v[114:117], v[190:193], v[26:29]
	v_mfma_i32_16x16x64_i8 v[14:17], v[126:129], v[190:193], v[14:17]
	v_mfma_i32_16x16x64_i8 v[14:17], v[178:181], v[194:197], v[14:17]
	v_mfma_i32_16x16x64_i8 v[6:9], v[178:181], v[210:213], v[6:9]
	v_mfma_i32_16x16x64_i8 v[6:9], v[126:129], v[198:201], v[6:9]
	v_mfma_i32_16x16x64_i8 v[18:21], v[114:117], v[198:201], v[18:21]
	v_mfma_i32_16x16x64_i8 v[18:21], v[118:121], v[210:213], v[18:21]
	v_mfma_i32_16x16x64_i8 v[10:13], v[118:121], v[218:221], v[10:13]
	v_mfma_i32_16x16x64_i8 v[10:13], v[114:117], v[214:217], v[10:13]
	s_barrier
	s_add_i32 s10, s10, 2
	s_add_u32 s69, s69, 0x100
	s_addc_u32 s68, s68, 0
	s_cmp_gt_u32 s10, 13
	s_mov_b64 s[8:9], s[84:85]
	s_cbranch_scc0 .LBB0_291
